# EpiRes: residual XB loads hoisted to epilogue start (14 of 16 round trips removed)
# speedup vs baseline: 1.0328x; 1.0067x over previous
;     __device__ __forceinline__ void operator()(const f32x4 (&acc)[2][2][4][2], const Unit& u, int wr, int wc, int fr, int fq) const {
;         const int row0 = u.pm * BM + wr * 64 + fr, col0 = u.pn * BM + wc * 32 + 8 * fq;
; #pragma unroll
;         for (int ai = 0; ai < 2; ++ai)
; #pragma unroll
;             for (int m = 0; m < 4; ++m) {
;                 const int row = row0 + ai * HALF + m * 16;
;                 bf16_t* xb = XB + (size_t)row * 1024 + col0; float ss = 0.f;
; #pragma unroll
;                 for (int bj = 0; bj < 2; ++bj) {
;                     const u32x4 xw = *(const u32x4*)(xb + bj * HALF);
;                     f32x4 x0, x1;
;                     x0[0] = __uint_as_float(xw.x << 16); x0[1] = __uint_as_float(xw.x & 0xffff0000u); x0[2] = __uint_as_float(xw.y << 16); x0[3] = __uint_as_float(xw.y & 0xffff0000u);
;                     x1[0] = __uint_as_float(xw.z << 16); x1[1] = __uint_as_float(xw.z & 0xffff0000u); x1[2] = __uint_as_float(xw.w << 16); x1[3] = __uint_as_float(xw.w & 0xffff0000u);
;                     x0 = x0 + acc[ai][bj][m][0] * alpha; x1 = x1 + acc[ai][bj][m][1] * alpha;
;                     if (OUT) { float* xr = OUT + (size_t)row * 1024 + col0 + bj * HALF; __builtin_nontemporal_store(x0, (f32x4*)xr); __builtin_nontemporal_store(x1, (f32x4*)(xr + 4)); }
.LBB0_1052:
	v_lshl_add_u32 v144, s56, 8, v148
	v_ashrrev_i32_e32 v145, 31, v144
	v_lshl_or_b32 v142, s28, 8, v150
	v_lshlrev_b64 v[128:129], 11, v[144:145]
	v_ashrrev_i32_e32 v143, 31, v142
	v_lshl_add_u64 v[128:129], s[24:25], 0, v[128:129]
	v_lshl_add_u64 v[146:147], v[142:143], 1, v[128:129]
	v_add_co_u32_e32 v152, vcc, 0x8000, v146
	s_nop 1
	v_addc_co_u32_e32 v153, vcc, 0, v147, vcc
	global_load_dwordx4 v[160:163], v[152:153], off
	global_load_dwordx4 v[164:167], v[152:153], off offset:256
	v_add_co_u32_e32 v152, vcc, 0x8000, v152
	s_nop 1
	v_addc_co_u32_e32 v153, vcc, 0, v153, vcc
	global_load_dwordx4 v[172:175], v[152:153], off
	global_load_dwordx4 v[176:179], v[152:153], off offset:256
	v_add_co_u32_e32 v152, vcc, 0x8000, v152
	s_nop 1
	v_addc_co_u32_e32 v153, vcc, 0, v153, vcc
	global_load_dwordx4 v[180:183], v[152:153], off
	global_load_dwordx4 v[184:187], v[152:153], off offset:256
	v_add_co_u32_e32 v152, vcc, 0x28000, v152
	s_nop 1
	v_addc_co_u32_e32 v153, vcc, 0, v153, vcc
	global_load_dwordx4 v[188:191], v[152:153], off
	global_load_dwordx4 v[192:195], v[152:153], off offset:256
	v_add_co_u32_e32 v152, vcc, 0x8000, v152
	s_nop 1
	v_addc_co_u32_e32 v153, vcc, 0, v153, vcc
	global_load_dwordx4 v[210:213], v[152:153], off
	global_load_dwordx4 v[218:221], v[152:153], off offset:256
	v_add_co_u32_e32 v152, vcc, 0x8000, v152
	s_nop 1
	v_addc_co_u32_e32 v153, vcc, 0, v153, vcc
	global_load_dwordx4 v[222:225], v[152:153], off
	global_load_dwordx4 v[226:229], v[152:153], off offset:256
	v_add_co_u32_e32 v152, vcc, 0x8000, v152
	s_nop 1
	v_addc_co_u32_e32 v153, vcc, 0, v153, vcc
	global_load_dwordx4 v[230:233], v[152:153], off
	global_load_dwordx4 v[234:237], v[152:153], off offset:256
	global_load_dwordx4 v[128:131], v[146:147], off
	v_cndmask_b32_e64 v152, 0, 1, s[80:81]
	v_cmp_ne_u32_e64 s[42:43], 1, v152
	v_lshlrev_b64 v[152:153], 10, v[144:145]
	s_mov_b64 s[44:45], -1
	s_andn2_b64 vcc, exec, s[80:81]
	s_waitcnt vmcnt(0)
	v_lshlrev_b32_e32 v154, 16, v128
	v_and_b32_e32 v155, 0xffff0000, v128
	v_lshlrev_b32_e32 v128, 16, v129
	v_and_b32_e32 v129, 0xffff0000, v129
	v_lshlrev_b32_e32 v156, 16, v130
	v_and_b32_e32 v157, 0xffff0000, v130
	v_lshlrev_b32_e32 v158, 16, v131
	v_and_b32_e32 v159, 0xffff0000, v131
	v_pk_fma_f32 v[130:131], s[54:55], v[122:123], v[128:129]
	v_pk_fma_f32 v[128:129], s[74:75], v[120:121], v[154:155]
	v_pk_fma_f32 v[122:123], s[54:55], v[126:127], v[158:159]
	v_pk_fma_f32 v[120:121], s[74:75], v[124:125], v[156:157]
	v_lshl_add_u64 v[124:125], v[152:153], 2, s[52:53]
	s_cbranch_vccnz .LBB0_1054
	v_lshl_add_u64 v[126:127], v[142:143], 2, v[124:125]
	s_mov_b64 s[44:45], 0
	global_store_dwordx4 v[126:127], v[128:131], off nt
	global_store_dwordx4 v[126:127], v[120:123], off offset:16 nt

;     __device__ __forceinline__ void operator()(const f32x4 (&acc)[2][2][4][2], const Unit& u, int wr, int wc, int fr, int fq) const {
;     ...
;                 const int row = row0 + ai * HALF + m * 16;
;                 bf16_t* xb = XB + (size_t)row * 1024 + col0; float ss = 0.f;
; #pragma unroll
;                 for (int bj = 0; bj < 2; ++bj) {
;                     const u32x4 xw = *(const u32x4*)(xb + bj * HALF);
;                     f32x4 x0, x1;
;                     x0[0] = __uint_as_float(xw.x << 16); x0[1] = __uint_as_float(xw.x & 0xffff0000u); x0[2] = __uint_as_float(xw.y << 16); x0[3] = __uint_as_float(xw.y & 0xffff0000u);
;                     x1[0] = __uint_as_float(xw.z << 16); x1[1] = __uint_as_float(xw.z & 0xffff0000u); x1[2] = __uint_as_float(xw.w << 16); x1[3] = __uint_as_float(xw.w & 0xffff0000u);
;                     x0 = x0 + acc[ai][bj][m][0] * alpha; x1 = x1 + acc[ai][bj][m][1] * alpha;
;                     if (OUT) { float* xr = OUT + (size_t)row * 1024 + col0 + bj * HALF; __builtin_nontemporal_store(x0, (f32x4*)xr); __builtin_nontemporal_store(x1, (f32x4*)(xr + 4)); }
.LBB0_1064:
	v_or_b32_e32 v112, 16, v144
	s_waitcnt lgkmcnt(0)
	v_ashrrev_i32_e32 v113, 31, v112
	v_lshlrev_b64 v[114:115], 11, v[112:113]
	v_lshl_add_u64 v[114:115], s[24:25], 0, v[114:115]
	v_lshl_add_u64 v[114:115], v[142:143], 1, v[114:115]
	v_mov_b32_e32 v116, v160
	v_mov_b32_e32 v117, v161
	v_mov_b32_e32 v118, v162
	v_mov_b32_e32 v119, v163
	v_lshlrev_b64 v[120:121], 10, v[112:113]
	s_mov_b64 s[58:59], -1
	s_and_b64 vcc, exec, s[42:43]
	v_lshlrev_b32_e32 v122, 16, v116
	v_and_b32_e32 v123, 0xffff0000, v116
	v_lshlrev_b32_e32 v116, 16, v117
	v_and_b32_e32 v117, 0xffff0000, v117
	v_lshlrev_b32_e32 v124, 16, v118
	v_and_b32_e32 v125, 0xffff0000, v118
	v_lshlrev_b32_e32 v118, 16, v119
	v_and_b32_e32 v119, 0xffff0000, v119
	v_pk_fma_f32 v[110:111], s[54:55], v[110:111], v[116:117]
	v_pk_fma_f32 v[108:109], s[74:75], v[108:109], v[122:123]
	v_pk_fma_f32 v[106:107], s[54:55], v[106:107], v[118:119]
	v_pk_fma_f32 v[104:105], s[74:75], v[104:105], v[124:125]
	v_lshl_add_u64 v[116:117], v[120:121], 2, s[52:53]
	s_cbranch_vccnz .LBB0_1066
	v_lshl_add_u64 v[118:119], v[142:143], 2, v[116:117]
	s_mov_b64 s[58:59], 0
	global_store_dwordx4 v[118:119], v[108:111], off nt
	global_store_dwordx4 v[118:119], v[104:107], off offset:16 nt

;     __device__ __forceinline__ void operator()(const f32x4 (&acc)[2][2][4][2], const Unit& u, int wr, int wc, int fr, int fq) const {
;     ...
;                 const int row = row0 + ai * HALF + m * 16;
;                 bf16_t* xb = XB + (size_t)row * 1024 + col0; float ss = 0.f;
; #pragma unroll
;                 for (int bj = 0; bj < 2; ++bj) {
;                     const u32x4 xw = *(const u32x4*)(xb + bj * HALF);
;                     f32x4 x0, x1;
;                     x0[0] = __uint_as_float(xw.x << 16); x0[1] = __uint_as_float(xw.x & 0xffff0000u); x0[2] = __uint_as_float(xw.y << 16); x0[3] = __uint_as_float(xw.y & 0xffff0000u);
;                     x1[0] = __uint_as_float(xw.z << 16); x1[1] = __uint_as_float(xw.z & 0xffff0000u); x1[2] = __uint_as_float(xw.w << 16); x1[3] = __uint_as_float(xw.w & 0xffff0000u);
;                     x0 = x0 + acc[ai][bj][m][0] * alpha; x1 = x1 + acc[ai][bj][m][1] * alpha;
;                     if (OUT) { float* xr = OUT + (size_t)row * 1024 + col0 + bj * HALF; __builtin_nontemporal_store(x0, (f32x4*)xr); __builtin_nontemporal_store(x1, (f32x4*)(xr + 4)); }
.LBB0_1068:
	v_mov_b32_e32 v104, v164
	v_mov_b32_e32 v105, v165
	v_mov_b32_e32 v106, v166
	v_mov_b32_e32 v107, v167
	s_and_b64 vcc, exec, s[42:43]
	s_mov_b64 s[58:59], -1
	v_lshlrev_b32_e32 v108, 16, v104
	v_and_b32_e32 v109, 0xffff0000, v104
	v_lshlrev_b32_e32 v104, 16, v105
	v_and_b32_e32 v105, 0xffff0000, v105
	v_lshlrev_b32_e32 v110, 16, v106
	v_and_b32_e32 v111, 0xffff0000, v106
	v_lshlrev_b32_e32 v106, 16, v107
	v_and_b32_e32 v107, 0xffff0000, v107
	v_pk_fma_f32 v[102:103], s[54:55], v[102:103], v[104:105]
	v_pk_fma_f32 v[100:101], s[74:75], v[100:101], v[108:109]
	v_pk_fma_f32 v[98:99], s[54:55], v[98:99], v[106:107]
	v_pk_fma_f32 v[96:97], s[74:75], v[96:97], v[110:111]
	s_cbranch_vccnz .LBB0_1071
	v_lshl_add_u64 v[104:105], v[142:143], 2, v[116:117]
	global_store_dwordx4 v[104:105], v[100:103], off offset:512 nt
	global_store_dwordx4 v[104:105], v[96:99], off offset:528 nt
	s_cbranch_execz .LBB0_1072

;     __device__ __forceinline__ void operator()(const f32x4 (&acc)[2][2][4][2], const Unit& u, int wr, int wc, int fr, int fq) const {
;     ...
;                 const int row = row0 + ai * HALF + m * 16;
;                 bf16_t* xb = XB + (size_t)row * 1024 + col0; float ss = 0.f;
; #pragma unroll
;                 for (int bj = 0; bj < 2; ++bj) {
;                     const u32x4 xw = *(const u32x4*)(xb + bj * HALF);
;                     f32x4 x0, x1;
;                     x0[0] = __uint_as_float(xw.x << 16); x0[1] = __uint_as_float(xw.x & 0xffff0000u); x0[2] = __uint_as_float(xw.y << 16); x0[3] = __uint_as_float(xw.y & 0xffff0000u);
;                     x1[0] = __uint_as_float(xw.z << 16); x1[1] = __uint_as_float(xw.z & 0xffff0000u); x1[2] = __uint_as_float(xw.w << 16); x1[3] = __uint_as_float(xw.w & 0xffff0000u);
;                     x0 = x0 + acc[ai][bj][m][0] * alpha; x1 = x1 + acc[ai][bj][m][1] * alpha;
;                     if (OUT) { float* xr = OUT + (size_t)row * 1024 + col0 + bj * HALF; __builtin_nontemporal_store(x0, (f32x4*)xr); __builtin_nontemporal_store(x1, (f32x4*)(xr + 4)); }
.LBB0_1076:
	v_or_b32_e32 v96, 32, v144
	s_waitcnt lgkmcnt(0)
	v_ashrrev_i32_e32 v97, 31, v96
	v_lshlrev_b64 v[98:99], 11, v[96:97]
	v_lshl_add_u64 v[98:99], s[24:25], 0, v[98:99]
	v_lshl_add_u64 v[98:99], v[142:143], 1, v[98:99]
	v_mov_b32_e32 v100, v172
	v_mov_b32_e32 v101, v173
	v_mov_b32_e32 v102, v174
	v_mov_b32_e32 v103, v175
	v_lshlrev_b64 v[104:105], 10, v[96:97]
	s_mov_b64 s[58:59], -1
	s_and_b64 vcc, exec, s[42:43]
	v_lshlrev_b32_e32 v106, 16, v100
	v_and_b32_e32 v107, 0xffff0000, v100
	v_lshlrev_b32_e32 v100, 16, v101
	v_and_b32_e32 v101, 0xffff0000, v101
	v_lshlrev_b32_e32 v108, 16, v102
	v_and_b32_e32 v109, 0xffff0000, v102
	v_lshlrev_b32_e32 v102, 16, v103
	v_and_b32_e32 v103, 0xffff0000, v103
	v_pk_fma_f32 v[94:95], s[54:55], v[94:95], v[100:101]
	v_pk_fma_f32 v[92:93], s[74:75], v[92:93], v[106:107]
	v_pk_fma_f32 v[90:91], s[54:55], v[90:91], v[102:103]
	v_pk_fma_f32 v[88:89], s[74:75], v[88:89], v[108:109]
	v_lshl_add_u64 v[100:101], v[104:105], 2, s[52:53]
	s_cbranch_vccnz .LBB0_1078
	v_lshl_add_u64 v[102:103], v[142:143], 2, v[100:101]
	s_mov_b64 s[58:59], 0
	global_store_dwordx4 v[102:103], v[92:95], off nt
	global_store_dwordx4 v[102:103], v[88:91], off offset:16 nt

;     __device__ __forceinline__ void operator()(const f32x4 (&acc)[2][2][4][2], const Unit& u, int wr, int wc, int fr, int fq) const {
;     ...
;                 const int row = row0 + ai * HALF + m * 16;
;                 bf16_t* xb = XB + (size_t)row * 1024 + col0; float ss = 0.f;
; #pragma unroll
;                 for (int bj = 0; bj < 2; ++bj) {
;                     const u32x4 xw = *(const u32x4*)(xb + bj * HALF);
;                     f32x4 x0, x1;
;                     x0[0] = __uint_as_float(xw.x << 16); x0[1] = __uint_as_float(xw.x & 0xffff0000u); x0[2] = __uint_as_float(xw.y << 16); x0[3] = __uint_as_float(xw.y & 0xffff0000u);
;                     x1[0] = __uint_as_float(xw.z << 16); x1[1] = __uint_as_float(xw.z & 0xffff0000u); x1[2] = __uint_as_float(xw.w << 16); x1[3] = __uint_as_float(xw.w & 0xffff0000u);
;                     x0 = x0 + acc[ai][bj][m][0] * alpha; x1 = x1 + acc[ai][bj][m][1] * alpha;
;                     if (OUT) { float* xr = OUT + (size_t)row * 1024 + col0 + bj * HALF; __builtin_nontemporal_store(x0, (f32x4*)xr); __builtin_nontemporal_store(x1, (f32x4*)(xr + 4)); }
.LBB0_1080:
	v_mov_b32_e32 v88, v176
	v_mov_b32_e32 v89, v177
	v_mov_b32_e32 v90, v178
	v_mov_b32_e32 v91, v179
	s_and_b64 vcc, exec, s[42:43]
	s_mov_b64 s[58:59], -1
	v_lshlrev_b32_e32 v92, 16, v88
	v_and_b32_e32 v93, 0xffff0000, v88
	v_lshlrev_b32_e32 v88, 16, v89
	v_and_b32_e32 v89, 0xffff0000, v89
	v_lshlrev_b32_e32 v94, 16, v90
	v_and_b32_e32 v95, 0xffff0000, v90
	v_lshlrev_b32_e32 v90, 16, v91
	v_and_b32_e32 v91, 0xffff0000, v91
	v_pk_fma_f32 v[86:87], s[54:55], v[86:87], v[88:89]
	v_pk_fma_f32 v[84:85], s[74:75], v[84:85], v[92:93]
	v_pk_fma_f32 v[82:83], s[54:55], v[82:83], v[90:91]
	v_pk_fma_f32 v[80:81], s[74:75], v[80:81], v[94:95]
	s_cbranch_vccnz .LBB0_1083
	v_lshl_add_u64 v[88:89], v[142:143], 2, v[100:101]
	global_store_dwordx4 v[88:89], v[84:87], off offset:512 nt
	global_store_dwordx4 v[88:89], v[80:83], off offset:528 nt
	s_cbranch_execz .LBB0_1084

;     __device__ __forceinline__ void operator()(const f32x4 (&acc)[2][2][4][2], const Unit& u, int wr, int wc, int fr, int fq) const {
;     ...
;                 const int row = row0 + ai * HALF + m * 16;
;                 bf16_t* xb = XB + (size_t)row * 1024 + col0; float ss = 0.f;
; #pragma unroll
;                 for (int bj = 0; bj < 2; ++bj) {
;                     const u32x4 xw = *(const u32x4*)(xb + bj * HALF);
;                     f32x4 x0, x1;
;                     x0[0] = __uint_as_float(xw.x << 16); x0[1] = __uint_as_float(xw.x & 0xffff0000u); x0[2] = __uint_as_float(xw.y << 16); x0[3] = __uint_as_float(xw.y & 0xffff0000u);
;                     x1[0] = __uint_as_float(xw.z << 16); x1[1] = __uint_as_float(xw.z & 0xffff0000u); x1[2] = __uint_as_float(xw.w << 16); x1[3] = __uint_as_float(xw.w & 0xffff0000u);
;                     x0 = x0 + acc[ai][bj][m][0] * alpha; x1 = x1 + acc[ai][bj][m][1] * alpha;
;                     if (OUT) { float* xr = OUT + (size_t)row * 1024 + col0 + bj * HALF; __builtin_nontemporal_store(x0, (f32x4*)xr); __builtin_nontemporal_store(x1, (f32x4*)(xr + 4)); }
.LBB0_1088:
	v_or_b32_e32 v80, 48, v144
	s_waitcnt lgkmcnt(0)
	v_ashrrev_i32_e32 v81, 31, v80
	v_lshlrev_b64 v[82:83], 11, v[80:81]
	v_lshl_add_u64 v[82:83], s[24:25], 0, v[82:83]
	v_lshl_add_u64 v[82:83], v[142:143], 1, v[82:83]
	v_mov_b32_e32 v84, v180
	v_mov_b32_e32 v85, v181
	v_mov_b32_e32 v86, v182
	v_mov_b32_e32 v87, v183
	v_lshlrev_b64 v[88:89], 10, v[80:81]
	s_mov_b64 s[58:59], -1
	s_and_b64 vcc, exec, s[42:43]
	v_lshlrev_b32_e32 v90, 16, v84
	v_and_b32_e32 v91, 0xffff0000, v84
	v_lshlrev_b32_e32 v84, 16, v85
	v_and_b32_e32 v85, 0xffff0000, v85
	v_lshlrev_b32_e32 v92, 16, v86
	v_and_b32_e32 v93, 0xffff0000, v86
	v_lshlrev_b32_e32 v86, 16, v87
	v_and_b32_e32 v87, 0xffff0000, v87
	v_pk_fma_f32 v[78:79], s[54:55], v[78:79], v[84:85]
	v_pk_fma_f32 v[76:77], s[74:75], v[76:77], v[90:91]
	v_pk_fma_f32 v[74:75], s[54:55], v[74:75], v[86:87]
	v_pk_fma_f32 v[72:73], s[74:75], v[72:73], v[92:93]
	v_lshl_add_u64 v[84:85], v[88:89], 2, s[52:53]
	s_cbranch_vccnz .LBB0_1090
	v_lshl_add_u64 v[86:87], v[142:143], 2, v[84:85]
	s_mov_b64 s[58:59], 0
	global_store_dwordx4 v[86:87], v[76:79], off nt
	global_store_dwordx4 v[86:87], v[72:75], off offset:16 nt

;     __device__ __forceinline__ void operator()(const f32x4 (&acc)[2][2][4][2], const Unit& u, int wr, int wc, int fr, int fq) const {
;     ...
;                 const int row = row0 + ai * HALF + m * 16;
;                 bf16_t* xb = XB + (size_t)row * 1024 + col0; float ss = 0.f;
; #pragma unroll
;                 for (int bj = 0; bj < 2; ++bj) {
;                     const u32x4 xw = *(const u32x4*)(xb + bj * HALF);
;                     f32x4 x0, x1;
;                     x0[0] = __uint_as_float(xw.x << 16); x0[1] = __uint_as_float(xw.x & 0xffff0000u); x0[2] = __uint_as_float(xw.y << 16); x0[3] = __uint_as_float(xw.y & 0xffff0000u);
;                     x1[0] = __uint_as_float(xw.z << 16); x1[1] = __uint_as_float(xw.z & 0xffff0000u); x1[2] = __uint_as_float(xw.w << 16); x1[3] = __uint_as_float(xw.w & 0xffff0000u);
;                     x0 = x0 + acc[ai][bj][m][0] * alpha; x1 = x1 + acc[ai][bj][m][1] * alpha;
;                     if (OUT) { float* xr = OUT + (size_t)row * 1024 + col0 + bj * HALF; __builtin_nontemporal_store(x0, (f32x4*)xr); __builtin_nontemporal_store(x1, (f32x4*)(xr + 4)); }
.LBB0_1092:
	v_mov_b32_e32 v72, v184
	v_mov_b32_e32 v73, v185
	v_mov_b32_e32 v74, v186
	v_mov_b32_e32 v75, v187
	s_and_b64 vcc, exec, s[42:43]
	s_mov_b64 s[58:59], -1
	v_lshlrev_b32_e32 v76, 16, v72
	v_and_b32_e32 v77, 0xffff0000, v72
	v_lshlrev_b32_e32 v72, 16, v73
	v_and_b32_e32 v73, 0xffff0000, v73
	v_lshlrev_b32_e32 v78, 16, v74
	v_and_b32_e32 v79, 0xffff0000, v74
	v_lshlrev_b32_e32 v74, 16, v75
	v_and_b32_e32 v75, 0xffff0000, v75
	v_pk_fma_f32 v[70:71], s[54:55], v[70:71], v[72:73]
	v_pk_fma_f32 v[68:69], s[74:75], v[68:69], v[76:77]
	v_pk_fma_f32 v[66:67], s[54:55], v[66:67], v[74:75]
	v_pk_fma_f32 v[64:65], s[74:75], v[64:65], v[78:79]
	s_cbranch_vccnz .LBB0_1095
	v_lshl_add_u64 v[72:73], v[142:143], 2, v[84:85]
	global_store_dwordx4 v[72:73], v[68:71], off offset:512 nt
	global_store_dwordx4 v[72:73], v[64:67], off offset:528 nt
	s_cbranch_execz .LBB0_1096

;     __device__ __forceinline__ void operator()(const f32x4 (&acc)[2][2][4][2], const Unit& u, int wr, int wc, int fr, int fq) const {
;     ...
;                 const int row = row0 + ai * HALF + m * 16;
;                 bf16_t* xb = XB + (size_t)row * 1024 + col0; float ss = 0.f;
; #pragma unroll
;                 for (int bj = 0; bj < 2; ++bj) {
;                     const u32x4 xw = *(const u32x4*)(xb + bj * HALF);
;                     f32x4 x0, x1;
;                     x0[0] = __uint_as_float(xw.x << 16); x0[1] = __uint_as_float(xw.x & 0xffff0000u); x0[2] = __uint_as_float(xw.y << 16); x0[3] = __uint_as_float(xw.y & 0xffff0000u);
;                     x1[0] = __uint_as_float(xw.z << 16); x1[1] = __uint_as_float(xw.z & 0xffff0000u); x1[2] = __uint_as_float(xw.w << 16); x1[3] = __uint_as_float(xw.w & 0xffff0000u);
;                     x0 = x0 + acc[ai][bj][m][0] * alpha; x1 = x1 + acc[ai][bj][m][1] * alpha;
;                     if (OUT) { float* xr = OUT + (size_t)row * 1024 + col0 + bj * HALF; __builtin_nontemporal_store(x0, (f32x4*)xr); __builtin_nontemporal_store(x1, (f32x4*)(xr + 4)); }
.LBB0_1100:
	v_add_u32_e32 v64, 0x80, v144
	s_waitcnt lgkmcnt(0)
	v_ashrrev_i32_e32 v65, 31, v64
	v_lshlrev_b64 v[66:67], 11, v[64:65]
	v_lshl_add_u64 v[66:67], s[24:25], 0, v[66:67]
	v_lshl_add_u64 v[66:67], v[142:143], 1, v[66:67]
	v_mov_b32_e32 v68, v188
	v_mov_b32_e32 v69, v189
	v_mov_b32_e32 v70, v190
	v_mov_b32_e32 v71, v191
	v_lshlrev_b64 v[72:73], 10, v[64:65]
	s_mov_b64 s[58:59], -1
	s_and_b64 vcc, exec, s[42:43]
	v_lshlrev_b32_e32 v74, 16, v68
	v_and_b32_e32 v75, 0xffff0000, v68
	v_lshlrev_b32_e32 v68, 16, v69
	v_and_b32_e32 v69, 0xffff0000, v69
	v_lshlrev_b32_e32 v76, 16, v70
	v_and_b32_e32 v77, 0xffff0000, v70
	v_lshlrev_b32_e32 v70, 16, v71
	v_and_b32_e32 v71, 0xffff0000, v71
	v_pk_fma_f32 v[62:63], s[54:55], v[62:63], v[68:69]
	v_pk_fma_f32 v[60:61], s[74:75], v[60:61], v[74:75]
	v_pk_fma_f32 v[58:59], s[54:55], v[58:59], v[70:71]
	v_pk_fma_f32 v[56:57], s[74:75], v[56:57], v[76:77]
	v_lshl_add_u64 v[68:69], v[72:73], 2, s[52:53]
	s_cbranch_vccnz .LBB0_1102
	v_lshl_add_u64 v[70:71], v[142:143], 2, v[68:69]
	s_mov_b64 s[58:59], 0
	global_store_dwordx4 v[70:71], v[60:63], off nt
	global_store_dwordx4 v[70:71], v[56:59], off offset:16 nt

;     __device__ __forceinline__ void operator()(const f32x4 (&acc)[2][2][4][2], const Unit& u, int wr, int wc, int fr, int fq) const {
;     ...
;                 const int row = row0 + ai * HALF + m * 16;
;                 bf16_t* xb = XB + (size_t)row * 1024 + col0; float ss = 0.f;
; #pragma unroll
;                 for (int bj = 0; bj < 2; ++bj) {
;                     const u32x4 xw = *(const u32x4*)(xb + bj * HALF);
;                     f32x4 x0, x1;
;                     x0[0] = __uint_as_float(xw.x << 16); x0[1] = __uint_as_float(xw.x & 0xffff0000u); x0[2] = __uint_as_float(xw.y << 16); x0[3] = __uint_as_float(xw.y & 0xffff0000u);
;                     x1[0] = __uint_as_float(xw.z << 16); x1[1] = __uint_as_float(xw.z & 0xffff0000u); x1[2] = __uint_as_float(xw.w << 16); x1[3] = __uint_as_float(xw.w & 0xffff0000u);
;                     x0 = x0 + acc[ai][bj][m][0] * alpha; x1 = x1 + acc[ai][bj][m][1] * alpha;
;                     if (OUT) { float* xr = OUT + (size_t)row * 1024 + col0 + bj * HALF; __builtin_nontemporal_store(x0, (f32x4*)xr); __builtin_nontemporal_store(x1, (f32x4*)(xr + 4)); }
.LBB0_1104:
	v_mov_b32_e32 v56, v192
	v_mov_b32_e32 v57, v193
	v_mov_b32_e32 v58, v194
	v_mov_b32_e32 v59, v195
	s_and_b64 vcc, exec, s[42:43]
	s_mov_b64 s[58:59], -1
	v_lshlrev_b32_e32 v60, 16, v56
	v_and_b32_e32 v61, 0xffff0000, v56
	v_lshlrev_b32_e32 v56, 16, v57
	v_and_b32_e32 v57, 0xffff0000, v57
	v_lshlrev_b32_e32 v62, 16, v58
	v_and_b32_e32 v63, 0xffff0000, v58
	v_lshlrev_b32_e32 v58, 16, v59
	v_and_b32_e32 v59, 0xffff0000, v59
	v_pk_fma_f32 v[54:55], s[54:55], v[54:55], v[56:57]
	v_pk_fma_f32 v[52:53], s[74:75], v[52:53], v[60:61]
	v_pk_fma_f32 v[50:51], s[54:55], v[50:51], v[58:59]
	v_pk_fma_f32 v[48:49], s[74:75], v[48:49], v[62:63]
	s_cbranch_vccnz .LBB0_1107
	v_lshl_add_u64 v[56:57], v[142:143], 2, v[68:69]
	global_store_dwordx4 v[56:57], v[52:55], off offset:512 nt
	global_store_dwordx4 v[56:57], v[48:51], off offset:528 nt
	s_cbranch_execz .LBB0_1108

;     __device__ __forceinline__ void operator()(const f32x4 (&acc)[2][2][4][2], const Unit& u, int wr, int wc, int fr, int fq) const {
;     ...
;                 const int row = row0 + ai * HALF + m * 16;
;                 bf16_t* xb = XB + (size_t)row * 1024 + col0; float ss = 0.f;
; #pragma unroll
;                 for (int bj = 0; bj < 2; ++bj) {
;                     const u32x4 xw = *(const u32x4*)(xb + bj * HALF);
;                     f32x4 x0, x1;
;                     x0[0] = __uint_as_float(xw.x << 16); x0[1] = __uint_as_float(xw.x & 0xffff0000u); x0[2] = __uint_as_float(xw.y << 16); x0[3] = __uint_as_float(xw.y & 0xffff0000u);
;                     x1[0] = __uint_as_float(xw.z << 16); x1[1] = __uint_as_float(xw.z & 0xffff0000u); x1[2] = __uint_as_float(xw.w << 16); x1[3] = __uint_as_float(xw.w & 0xffff0000u);
;                     x0 = x0 + acc[ai][bj][m][0] * alpha; x1 = x1 + acc[ai][bj][m][1] * alpha;
;                     if (OUT) { float* xr = OUT + (size_t)row * 1024 + col0 + bj * HALF; __builtin_nontemporal_store(x0, (f32x4*)xr); __builtin_nontemporal_store(x1, (f32x4*)(xr + 4)); }
.LBB0_1112:
	v_add_u32_e32 v48, 0x90, v144
	s_waitcnt lgkmcnt(0)
	v_ashrrev_i32_e32 v49, 31, v48
	v_lshlrev_b64 v[50:51], 11, v[48:49]
	v_lshl_add_u64 v[50:51], s[24:25], 0, v[50:51]
	v_lshl_add_u64 v[50:51], v[142:143], 1, v[50:51]
	v_mov_b32_e32 v52, v210
	v_mov_b32_e32 v53, v211
	v_mov_b32_e32 v54, v212
	v_mov_b32_e32 v55, v213
	v_lshlrev_b64 v[56:57], 10, v[48:49]
	s_mov_b64 s[58:59], -1
	s_and_b64 vcc, exec, s[42:43]
	v_lshlrev_b32_e32 v58, 16, v52
	v_and_b32_e32 v59, 0xffff0000, v52
	v_lshlrev_b32_e32 v52, 16, v53
	v_and_b32_e32 v53, 0xffff0000, v53
	v_lshlrev_b32_e32 v60, 16, v54
	v_and_b32_e32 v61, 0xffff0000, v54
	v_lshlrev_b32_e32 v54, 16, v55
	v_and_b32_e32 v55, 0xffff0000, v55
	v_pk_fma_f32 v[46:47], s[54:55], v[46:47], v[52:53]
	v_pk_fma_f32 v[44:45], s[74:75], v[44:45], v[58:59]
	v_pk_fma_f32 v[42:43], s[54:55], v[42:43], v[54:55]
	v_pk_fma_f32 v[40:41], s[74:75], v[40:41], v[60:61]
	v_lshl_add_u64 v[52:53], v[56:57], 2, s[52:53]
	s_cbranch_vccnz .LBB0_1114
	v_lshl_add_u64 v[54:55], v[142:143], 2, v[52:53]
	s_mov_b64 s[58:59], 0
	global_store_dwordx4 v[54:55], v[44:47], off nt
	global_store_dwordx4 v[54:55], v[40:43], off offset:16 nt

;     __device__ __forceinline__ void operator()(const f32x4 (&acc)[2][2][4][2], const Unit& u, int wr, int wc, int fr, int fq) const {
;     ...
;                 const int row = row0 + ai * HALF + m * 16;
;                 bf16_t* xb = XB + (size_t)row * 1024 + col0; float ss = 0.f;
; #pragma unroll
;                 for (int bj = 0; bj < 2; ++bj) {
;                     const u32x4 xw = *(const u32x4*)(xb + bj * HALF);
;                     f32x4 x0, x1;
;                     x0[0] = __uint_as_float(xw.x << 16); x0[1] = __uint_as_float(xw.x & 0xffff0000u); x0[2] = __uint_as_float(xw.y << 16); x0[3] = __uint_as_float(xw.y & 0xffff0000u);
;                     x1[0] = __uint_as_float(xw.z << 16); x1[1] = __uint_as_float(xw.z & 0xffff0000u); x1[2] = __uint_as_float(xw.w << 16); x1[3] = __uint_as_float(xw.w & 0xffff0000u);
;                     x0 = x0 + acc[ai][bj][m][0] * alpha; x1 = x1 + acc[ai][bj][m][1] * alpha;
;                     if (OUT) { float* xr = OUT + (size_t)row * 1024 + col0 + bj * HALF; __builtin_nontemporal_store(x0, (f32x4*)xr); __builtin_nontemporal_store(x1, (f32x4*)(xr + 4)); }
.LBB0_1116:
	v_mov_b32_e32 v40, v218
	v_mov_b32_e32 v41, v219
	v_mov_b32_e32 v42, v220
	v_mov_b32_e32 v43, v221
	s_and_b64 vcc, exec, s[42:43]
	s_mov_b64 s[58:59], -1
	v_lshlrev_b32_e32 v44, 16, v40
	v_and_b32_e32 v45, 0xffff0000, v40
	v_lshlrev_b32_e32 v40, 16, v41
	v_and_b32_e32 v41, 0xffff0000, v41
	v_lshlrev_b32_e32 v46, 16, v42
	v_and_b32_e32 v47, 0xffff0000, v42
	v_lshlrev_b32_e32 v42, 16, v43
	v_and_b32_e32 v43, 0xffff0000, v43
	v_pk_fma_f32 v[38:39], s[54:55], v[38:39], v[40:41]
	v_pk_fma_f32 v[36:37], s[74:75], v[36:37], v[44:45]
	v_pk_fma_f32 v[34:35], s[54:55], v[34:35], v[42:43]
	v_pk_fma_f32 v[32:33], s[74:75], v[32:33], v[46:47]
	s_cbranch_vccnz .LBB0_1119
	v_lshl_add_u64 v[40:41], v[142:143], 2, v[52:53]
	global_store_dwordx4 v[40:41], v[36:39], off offset:512 nt
	global_store_dwordx4 v[40:41], v[32:35], off offset:528 nt
	s_cbranch_execz .LBB0_1120

;     __device__ __forceinline__ void operator()(const f32x4 (&acc)[2][2][4][2], const Unit& u, int wr, int wc, int fr, int fq) const {
;     ...
;                 const int row = row0 + ai * HALF + m * 16;
;                 bf16_t* xb = XB + (size_t)row * 1024 + col0; float ss = 0.f;
; #pragma unroll
;                 for (int bj = 0; bj < 2; ++bj) {
;                     const u32x4 xw = *(const u32x4*)(xb + bj * HALF);
;                     f32x4 x0, x1;
;                     x0[0] = __uint_as_float(xw.x << 16); x0[1] = __uint_as_float(xw.x & 0xffff0000u); x0[2] = __uint_as_float(xw.y << 16); x0[3] = __uint_as_float(xw.y & 0xffff0000u);
;                     x1[0] = __uint_as_float(xw.z << 16); x1[1] = __uint_as_float(xw.z & 0xffff0000u); x1[2] = __uint_as_float(xw.w << 16); x1[3] = __uint_as_float(xw.w & 0xffff0000u);
;                     x0 = x0 + acc[ai][bj][m][0] * alpha; x1 = x1 + acc[ai][bj][m][1] * alpha;
;                     if (OUT) { float* xr = OUT + (size_t)row * 1024 + col0 + bj * HALF; __builtin_nontemporal_store(x0, (f32x4*)xr); __builtin_nontemporal_store(x1, (f32x4*)(xr + 4)); }
.LBB0_1124:
	v_add_u32_e32 v32, 0xa0, v144
	s_waitcnt lgkmcnt(0)
	v_ashrrev_i32_e32 v33, 31, v32
	v_lshlrev_b64 v[34:35], 11, v[32:33]
	v_lshl_add_u64 v[34:35], s[24:25], 0, v[34:35]
	v_lshl_add_u64 v[34:35], v[142:143], 1, v[34:35]
	v_mov_b32_e32 v36, v222
	v_mov_b32_e32 v37, v223
	v_mov_b32_e32 v38, v224
	v_mov_b32_e32 v39, v225
	v_lshlrev_b64 v[40:41], 10, v[32:33]
	s_mov_b64 s[58:59], -1
	s_and_b64 vcc, exec, s[42:43]
	v_lshlrev_b32_e32 v42, 16, v36
	v_and_b32_e32 v43, 0xffff0000, v36
	v_lshlrev_b32_e32 v36, 16, v37
	v_and_b32_e32 v37, 0xffff0000, v37
	v_lshlrev_b32_e32 v44, 16, v38
	v_and_b32_e32 v45, 0xffff0000, v38
	v_lshlrev_b32_e32 v38, 16, v39
	v_and_b32_e32 v39, 0xffff0000, v39
	v_pk_fma_f32 v[30:31], s[54:55], v[30:31], v[36:37]
	v_pk_fma_f32 v[28:29], s[74:75], v[28:29], v[42:43]
	v_pk_fma_f32 v[26:27], s[54:55], v[26:27], v[38:39]
	v_pk_fma_f32 v[24:25], s[74:75], v[24:25], v[44:45]
	v_lshl_add_u64 v[36:37], v[40:41], 2, s[52:53]
	s_cbranch_vccnz .LBB0_1126
	v_lshl_add_u64 v[38:39], v[142:143], 2, v[36:37]
	s_mov_b64 s[58:59], 0
	global_store_dwordx4 v[38:39], v[28:31], off nt
	global_store_dwordx4 v[38:39], v[24:27], off offset:16 nt

;     __device__ __forceinline__ void operator()(const f32x4 (&acc)[2][2][4][2], const Unit& u, int wr, int wc, int fr, int fq) const {
;     ...
;                 const int row = row0 + ai * HALF + m * 16;
;                 bf16_t* xb = XB + (size_t)row * 1024 + col0; float ss = 0.f;
; #pragma unroll
;                 for (int bj = 0; bj < 2; ++bj) {
;                     const u32x4 xw = *(const u32x4*)(xb + bj * HALF);
;                     f32x4 x0, x1;
;                     x0[0] = __uint_as_float(xw.x << 16); x0[1] = __uint_as_float(xw.x & 0xffff0000u); x0[2] = __uint_as_float(xw.y << 16); x0[3] = __uint_as_float(xw.y & 0xffff0000u);
;                     x1[0] = __uint_as_float(xw.z << 16); x1[1] = __uint_as_float(xw.z & 0xffff0000u); x1[2] = __uint_as_float(xw.w << 16); x1[3] = __uint_as_float(xw.w & 0xffff0000u);
;                     x0 = x0 + acc[ai][bj][m][0] * alpha; x1 = x1 + acc[ai][bj][m][1] * alpha;
;                     if (OUT) { float* xr = OUT + (size_t)row * 1024 + col0 + bj * HALF; __builtin_nontemporal_store(x0, (f32x4*)xr); __builtin_nontemporal_store(x1, (f32x4*)(xr + 4)); }
.LBB0_1128:
	v_mov_b32_e32 v24, v226
	v_mov_b32_e32 v25, v227
	v_mov_b32_e32 v26, v228
	v_mov_b32_e32 v27, v229
	s_and_b64 vcc, exec, s[42:43]
	s_mov_b64 s[58:59], -1
	v_lshlrev_b32_e32 v28, 16, v24
	v_and_b32_e32 v29, 0xffff0000, v24
	v_lshlrev_b32_e32 v24, 16, v25
	v_and_b32_e32 v25, 0xffff0000, v25
	v_lshlrev_b32_e32 v30, 16, v26
	v_and_b32_e32 v31, 0xffff0000, v26
	v_lshlrev_b32_e32 v26, 16, v27
	v_and_b32_e32 v27, 0xffff0000, v27
	v_pk_fma_f32 v[22:23], s[54:55], v[22:23], v[24:25]
	v_pk_fma_f32 v[20:21], s[74:75], v[20:21], v[28:29]
	v_pk_fma_f32 v[18:19], s[54:55], v[18:19], v[26:27]
	v_pk_fma_f32 v[16:17], s[74:75], v[16:17], v[30:31]
	s_cbranch_vccnz .LBB0_1131
	v_lshl_add_u64 v[24:25], v[142:143], 2, v[36:37]
	global_store_dwordx4 v[24:25], v[20:23], off offset:512 nt
	global_store_dwordx4 v[24:25], v[16:19], off offset:528 nt
	s_cbranch_execz .LBB0_1132

;     __device__ __forceinline__ void operator()(const f32x4 (&acc)[2][2][4][2], const Unit& u, int wr, int wc, int fr, int fq) const {
;     ...
;                 const int row = row0 + ai * HALF + m * 16;
;                 bf16_t* xb = XB + (size_t)row * 1024 + col0; float ss = 0.f;
; #pragma unroll
;                 for (int bj = 0; bj < 2; ++bj) {
;                     const u32x4 xw = *(const u32x4*)(xb + bj * HALF);
;                     f32x4 x0, x1;
;                     x0[0] = __uint_as_float(xw.x << 16); x0[1] = __uint_as_float(xw.x & 0xffff0000u); x0[2] = __uint_as_float(xw.y << 16); x0[3] = __uint_as_float(xw.y & 0xffff0000u);
;                     x1[0] = __uint_as_float(xw.z << 16); x1[1] = __uint_as_float(xw.z & 0xffff0000u); x1[2] = __uint_as_float(xw.w << 16); x1[3] = __uint_as_float(xw.w & 0xffff0000u);
;                     x0 = x0 + acc[ai][bj][m][0] * alpha; x1 = x1 + acc[ai][bj][m][1] * alpha;
;                     if (OUT) { float* xr = OUT + (size_t)row * 1024 + col0 + bj * HALF; __builtin_nontemporal_store(x0, (f32x4*)xr); __builtin_nontemporal_store(x1, (f32x4*)(xr + 4)); }
.LBB0_1136:
	v_add_u32_e32 v16, 0xb0, v144
	s_waitcnt lgkmcnt(0)
	v_ashrrev_i32_e32 v17, 31, v16
	v_lshlrev_b64 v[18:19], 11, v[16:17]
	v_lshl_add_u64 v[18:19], s[24:25], 0, v[18:19]
	v_lshl_add_u64 v[18:19], v[142:143], 1, v[18:19]
	v_mov_b32_e32 v20, v230
	v_mov_b32_e32 v21, v231
	v_mov_b32_e32 v22, v232
	v_mov_b32_e32 v23, v233
	v_lshlrev_b64 v[24:25], 10, v[16:17]
	s_mov_b64 s[58:59], -1
	s_and_b64 vcc, exec, s[42:43]
	v_lshlrev_b32_e32 v26, 16, v20
	v_and_b32_e32 v27, 0xffff0000, v20
	v_lshlrev_b32_e32 v20, 16, v21
	v_and_b32_e32 v21, 0xffff0000, v21
	v_lshlrev_b32_e32 v28, 16, v22
	v_and_b32_e32 v29, 0xffff0000, v22
	v_lshlrev_b32_e32 v22, 16, v23
	v_and_b32_e32 v23, 0xffff0000, v23
	v_pk_fma_f32 v[14:15], s[54:55], v[14:15], v[20:21]
	v_pk_fma_f32 v[12:13], s[74:75], v[12:13], v[26:27]
	v_pk_fma_f32 v[10:11], s[54:55], v[10:11], v[22:23]
	v_pk_fma_f32 v[8:9], s[74:75], v[8:9], v[28:29]
	v_lshl_add_u64 v[20:21], v[24:25], 2, s[52:53]
	s_cbranch_vccnz .LBB0_1138
	v_lshl_add_u64 v[22:23], v[142:143], 2, v[20:21]
	s_mov_b64 s[58:59], 0
	global_store_dwordx4 v[22:23], v[12:15], off nt
	global_store_dwordx4 v[22:23], v[8:11], off offset:16 nt

;     __device__ __forceinline__ void operator()(const f32x4 (&acc)[2][2][4][2], const Unit& u, int wr, int wc, int fr, int fq) const {
;     ...
;                 const int row = row0 + ai * HALF + m * 16;
;                 bf16_t* xb = XB + (size_t)row * 1024 + col0; float ss = 0.f;
; #pragma unroll
;                 for (int bj = 0; bj < 2; ++bj) {
;                     const u32x4 xw = *(const u32x4*)(xb + bj * HALF);
;                     f32x4 x0, x1;
;                     x0[0] = __uint_as_float(xw.x << 16); x0[1] = __uint_as_float(xw.x & 0xffff0000u); x0[2] = __uint_as_float(xw.y << 16); x0[3] = __uint_as_float(xw.y & 0xffff0000u);
;                     x1[0] = __uint_as_float(xw.z << 16); x1[1] = __uint_as_float(xw.z & 0xffff0000u); x1[2] = __uint_as_float(xw.w << 16); x1[3] = __uint_as_float(xw.w & 0xffff0000u);
;                     x0 = x0 + acc[ai][bj][m][0] * alpha; x1 = x1 + acc[ai][bj][m][1] * alpha;
;                     if (OUT) { float* xr = OUT + (size_t)row * 1024 + col0 + bj * HALF; __builtin_nontemporal_store(x0, (f32x4*)xr); __builtin_nontemporal_store(x1, (f32x4*)(xr + 4)); }
.LBB0_1140:
	v_mov_b32_e32 v8, v234
	v_mov_b32_e32 v9, v235
	v_mov_b32_e32 v10, v236
	v_mov_b32_e32 v11, v237
	s_and_b64 vcc, exec, s[42:43]
	s_mov_b64 s[42:43], -1
	v_lshlrev_b32_e32 v12, 16, v8
	v_and_b32_e32 v13, 0xffff0000, v8
	v_lshlrev_b32_e32 v8, 16, v9
	v_and_b32_e32 v9, 0xffff0000, v9
	v_lshlrev_b32_e32 v14, 16, v10
	v_and_b32_e32 v15, 0xffff0000, v10
	v_lshlrev_b32_e32 v10, 16, v11
	v_and_b32_e32 v11, 0xffff0000, v11
	v_pk_fma_f32 v[6:7], s[54:55], v[6:7], v[8:9]
	v_pk_fma_f32 v[4:5], s[74:75], v[4:5], v[12:13]
	v_pk_fma_f32 v[2:3], s[54:55], v[2:3], v[10:11]
	v_pk_fma_f32 v[0:1], s[74:75], v[0:1], v[14:15]
	s_cbranch_vccnz .LBB0_1144
	v_lshl_add_u64 v[8:9], v[142:143], 2, v[20:21]
	global_store_dwordx4 v[8:9], v[4:7], off offset:512 nt
	global_store_dwordx4 v[8:9], v[0:3], off offset:528 nt
	s_cbranch_execz .LBB0_1145
